# instruction selection: v_cvt_pk_bf16_f32 replaces the 6-op bit-trick RNE pair packing of the SGU mixing weights (96 sites) on v25
# speedup vs baseline: 1.0008x; 1.0008x over previous
.LBB0_406:
	v_cmp_le_u32_e32 vcc, v120, v124
	s_movk_i32 s10, 0x7fff
	s_mov_b32 s11, 0xffff0000
	s_waitcnt vmcnt(2)
	v_cndmask_b32_e32 v4, 0, v4, vcc
	v_cmp_lt_u32_e32 vcc, v120, v124
	v_cndmask_b32_e32 v5, 0, v5, vcc
	v_cvt_pk_bf16_f32 v4, v4, v5
	v_or_b32_e32 v5, 2, v120
	v_cmp_le_u32_e32 vcc, v5, v124
	v_lshl_add_u32 v119, v120, 1, s17
	s_movk_i32 s17, 0x110
	v_cndmask_b32_e32 v5, 0, v6, vcc
	v_or_b32_e32 v6, 3, v120
	v_cmp_le_u32_e32 vcc, v6, v124
	v_mad_u32_u24 v88, v118, s17, v119
	ds_read_b128 v[12:15], v88
	ds_read_b128 v[92:95], v88 offset:32
	v_cndmask_b32_e32 v6, 0, v7, vcc
	v_cvt_pk_bf16_f32 v5, v5, v6
	v_or_b32_e32 v6, 4, v120
	v_cmp_le_u32_e32 vcc, v6, v124
	v_or_b32_e32 v6, 5, v120
	v_lshlrev_b32_e32 v8, 2, v10
	v_cndmask_b32_e32 v0, 0, v0, vcc
	v_cmp_le_u32_e32 vcc, v6, v124
	v_cndmask_b32_e32 v1, 0, v1, vcc
	v_cvt_pk_bf16_f32 v6, v0, v1
	v_or_b32_e32 v0, 6, v120
	v_cmp_le_u32_e32 vcc, v0, v124
	v_or_b32_e32 v1, 7, v120
	v_or_b32_e32 v114, s18, v124
	v_cndmask_b32_e32 v0, 0, v2, vcc
	v_cmp_le_u32_e32 vcc, v1, v124
	v_cndmask_b32_e32 v1, 0, v3, vcc
	v_cvt_pk_bf16_f32 v7, v0, v1
	ds_read_b128 v[0:3], v88 offset:8704
	ds_read_b128 v[96:99], v88 offset:8736
	s_waitcnt lgkmcnt(1)
	v_mfma_f32_32x32x16_bf16 v[32:47], v[0:3], v[4:7], 0
	ds_read_b128 v[0:3], v88 offset:17408
	global_load_dword v68, v8, s[14:15]
	ds_read_b128 v[8:11], v88 offset:26112
	ds_read_b128 v[126:129], v88 offset:17440
	ds_read_b128 v[130:133], v88 offset:26144
	v_or_b32_e32 v88, 16, v120
	v_cmp_le_u32_e32 vcc, v88, v124
	s_movk_i32 s26, 0x1400
	v_mfma_f32_32x32x16_bf16 v[48:63], v[12:15], v[4:7], 0
	s_waitcnt vmcnt(1)
	v_cndmask_b32_e32 v84, 0, v84, vcc
	v_cmp_lt_u32_e32 vcc, v88, v124
	v_cndmask_b32_e32 v85, 0, v85, vcc
	v_cvt_pk_bf16_f32 v134, v84, v85
	v_or_b32_e32 v84, 18, v120
	v_cmp_le_u32_e32 vcc, v84, v124
	v_or_b32_e32 v85, 19, v120
	s_waitcnt lgkmcnt(3)
	v_mfma_f32_32x32x16_bf16 v[16:31], v[0:3], v[4:7], 0
	v_cndmask_b32_e32 v84, 0, v86, vcc
	v_cmp_le_u32_e32 vcc, v85, v124
	v_cndmask_b32_e32 v85, 0, v87, vcc
	v_cvt_pk_bf16_f32 v135, v84, v85
	v_or_b32_e32 v84, 20, v120
	v_cmp_le_u32_e32 vcc, v84, v124
	v_or_b32_e32 v84, 21, v120
	v_mov_b64_e32 v[0:1], s[22:23]
	v_cndmask_b32_e32 v80, 0, v80, vcc
	v_cmp_le_u32_e32 vcc, v84, v124
	v_cndmask_b32_e32 v81, 0, v81, vcc
	v_cvt_pk_bf16_f32 v136, v80, v81
	v_or_b32_e32 v80, 22, v120
	v_cmp_le_u32_e32 vcc, v80, v124
	v_or_b32_e32 v81, 23, v120
	v_mad_u64_u32 v[100:101], s[26:27], v114, s26, v[0:1]
	v_cndmask_b32_e32 v80, 0, v82, vcc
	v_cmp_le_u32_e32 vcc, v81, v124
	v_mov_b32_e32 v102, 0x1400
	v_cndmask_b32_e32 v81, 0, v83, vcc
	s_mov_b32 s17, 0
	v_mad_u32_u24 v101, s19, v102, v101
	v_mov_b32_e32 v121, 0
	v_cvt_pk_bf16_f32 v137, v80, v81
	v_lshl_add_u64 v[80:81], v[100:101], 0, s[16:17]
	v_lshl_add_u64 v[80:81], v[80:81], 0, v[120:121]
	v_mfma_f32_32x32x16_bf16 v[48:63], v[92:95], v[134:137], v[48:63]
	v_bfe_u32 v174, v224, 5, 1
	v_lshlrev_b32_e32 v174, 3, v174
	v_mov_b32_e32 v175, 0
	v_lshl_add_u64 v[172:173], v[80:81], 0, v[174:175]
	global_load_dwordx4 v[140:143], v[172:173], off offset:3072
	global_load_dwordx4 v[144:147], v[172:173], off offset:3104
	v_mul_u32_u24_e32 v118, 0x110, v118
	v_lshlrev_b32_e32 v88, 2, v115
	v_mov_b32_e32 v115, s19
	s_and_b64 vcc, exec, s[8:9]
	v_add_u32_e32 v121, v119, v118
	v_mfma_f32_32x32x16_bf16 v[32:47], v[96:99], v[134:137], v[32:47]
	global_load_dwordx4 v[148:151], v[172:173], off offset:3136
	global_load_dwordx4 v[152:155], v[172:173], off offset:3168
	global_load_dwordx4 v[156:159], v[172:173], off offset:3200
	global_load_dwordx4 v[160:163], v[172:173], off offset:3232
	global_load_dwordx4 v[164:167], v[172:173], off offset:3264
	global_load_dwordx4 v[168:171], v[172:173], off offset:3296
	s_nop 0
	s_waitcnt lgkmcnt(2)
	v_mfma_f32_32x32x16_bf16 v[0:15], v[8:11], v[4:7], 0
	s_waitcnt lgkmcnt(1)
	v_mfma_f32_32x32x16_bf16 v[16:31], v[126:129], v[134:137], v[16:31]
	s_waitcnt lgkmcnt(0)
	v_mfma_f32_32x32x16_bf16 v[0:15], v[130:133], v[134:137], v[0:15]
	s_cbranch_vccnz .LBB0_408
	v_or_b32_e32 v118, 32, v120
	v_cmp_le_u32_e32 vcc, v118, v124
	ds_read_b128 v[126:129], v121 offset:64
	s_nop 0
	v_cndmask_b32_e32 v76, 0, v76, vcc
	v_cmp_lt_u32_e32 vcc, v118, v124
	v_cndmask_b32_e32 v77, 0, v77, vcc
	v_cvt_pk_bf16_f32 v76, v76, v77
	v_or_b32_e32 v77, 34, v120
	v_cmp_le_u32_e32 vcc, v77, v124
	s_nop 1
	v_cndmask_b32_e32 v77, 0, v78, vcc
	v_or_b32_e32 v78, 35, v120
	v_cmp_le_u32_e32 vcc, v78, v124
	s_nop 1
	v_cndmask_b32_e32 v78, 0, v79, vcc
	v_cvt_pk_bf16_f32 v77, v77, v78
	v_or_b32_e32 v78, 36, v120
	v_cmp_le_u32_e32 vcc, v78, v124
	v_or_b32_e32 v78, 37, v120
	s_nop 0
	v_cndmask_b32_e32 v72, 0, v72, vcc
	v_cmp_le_u32_e32 vcc, v78, v124
	v_cndmask_b32_e32 v73, 0, v73, vcc
	v_cvt_pk_bf16_f32 v78, v72, v73
	v_or_b32_e32 v72, 38, v120
	v_cmp_le_u32_e32 vcc, v72, v124
	v_or_b32_e32 v73, 39, v120
	s_nop 0
	v_cndmask_b32_e32 v72, 0, v74, vcc
	v_cmp_le_u32_e32 vcc, v73, v124
	v_cndmask_b32_e32 v73, 0, v75, vcc
	v_cvt_pk_bf16_f32 v79, v72, v73
	ds_read_b128 v[72:75], v121 offset:8768
	s_waitcnt lgkmcnt(1)
	v_mfma_f32_32x32x16_bf16 v[48:63], v[126:129], v[76:79], v[48:63]
	s_waitcnt lgkmcnt(0)
	v_mfma_f32_32x32x16_bf16 v[32:47], v[72:75], v[76:79], v[32:47]
	ds_read_b128 v[72:75], v121 offset:17472
	ds_read_b128 v[126:129], v121 offset:26176
	s_waitcnt lgkmcnt(1)
	v_mfma_f32_32x32x16_bf16 v[16:31], v[72:75], v[76:79], v[16:31]
	s_waitcnt lgkmcnt(0)
	v_mfma_f32_32x32x16_bf16 v[0:15], v[126:129], v[76:79], v[0:15]
.LBB0_408:
	s_and_b64 vcc, exec, s[8:9]
	s_cbranch_vccnz .LBB0_410
	v_or_b32_e32 v72, 48, v120
	v_cmp_le_u32_e32 vcc, v72, v124
	s_movk_i32 s8, 0x7fff
	s_mov_b32 s9, 0xffff0000
	v_cndmask_b32_e32 v73, 0, v89, vcc
	v_cmp_lt_u32_e32 vcc, v72, v124
	v_cndmask_b32_e32 v69, 0, v69, vcc
	v_cvt_pk_bf16_f32 v72, v73, v69
	v_or_b32_e32 v69, 50, v120
	v_cmp_le_u32_e32 vcc, v69, v124
	ds_read_b128 v[76:79], v121 offset:96
	s_nop 0
	v_cndmask_b32_e32 v69, 0, v70, vcc
	v_or_b32_e32 v70, 51, v120
	v_cmp_le_u32_e32 vcc, v70, v124
	s_nop 1
	v_cndmask_b32_e32 v70, 0, v71, vcc
	v_cvt_pk_bf16_f32 v73, v69, v70
	v_or_b32_e32 v69, 52, v120
	v_cmp_le_u32_e32 vcc, v69, v124
	v_or_b32_e32 v69, 53, v120
	s_nop 0
	v_cndmask_b32_e32 v64, 0, v64, vcc
	v_cmp_le_u32_e32 vcc, v69, v124
	v_cndmask_b32_e32 v65, 0, v65, vcc
	v_cvt_pk_bf16_f32 v74, v64, v65
	v_or_b32_e32 v64, 54, v120
	v_cmp_le_u32_e32 vcc, v64, v124
	v_or_b32_e32 v65, 55, v120
	s_nop 0
	v_cndmask_b32_e32 v64, 0, v66, vcc
	v_cmp_le_u32_e32 vcc, v65, v124
	v_cndmask_b32_e32 v65, 0, v67, vcc
	v_cvt_pk_bf16_f32 v75, v64, v65
	ds_read_b128 v[64:67], v121 offset:8800
	s_waitcnt lgkmcnt(1)
	v_mfma_f32_32x32x16_bf16 v[48:63], v[76:79], v[72:75], v[48:63]
	s_waitcnt lgkmcnt(0)
	v_mfma_f32_32x32x16_bf16 v[32:47], v[64:67], v[72:75], v[32:47]
	ds_read_b128 v[64:67], v121 offset:17504
	ds_read_b128 v[76:79], v121 offset:26208
	s_waitcnt lgkmcnt(1)
	v_mfma_f32_32x32x16_bf16 v[16:31], v[64:67], v[72:75], v[16:31]
	s_waitcnt lgkmcnt(0)
	v_mfma_f32_32x32x16_bf16 v[0:15], v[76:79], v[72:75], v[0:15]

.LBB0_414:
	s_movk_i32 s12, 0x7fff
	s_waitcnt vmcnt(8)
	s_mov_b32 s13, 0xffff0000
	v_cvt_pk_bf16_f32 v116, v116, v117
	v_cvt_pk_bf16_f32 v117, v118, v119
	v_cvt_pk_bf16_f32 v118, v112, v113
	v_cvt_pk_bf16_f32 v119, v114, v115
	s_waitcnt vmcnt(6)
	v_cvt_pk_bf16_f32 v108, v108, v109
	v_cvt_pk_bf16_f32 v4, v4, v5
	v_cvt_pk_bf16_f32 v109, v110, v111
	v_cvt_pk_bf16_f32 v5, v6, v7
	ds_read_b128 v[8:11], v121
	ds_read_b128 v[126:129], v121 offset:32
	v_cvt_pk_bf16_f32 v110, v104, v105
	v_cvt_pk_bf16_f32 v6, v0, v1
	v_cvt_pk_bf16_f32 v111, v106, v107
	s_waitcnt vmcnt(4)
	v_cvt_pk_bf16_f32 v7, v2, v3
	ds_read_b128 v[0:3], v121 offset:8704
	ds_read_b128 v[130:133], v121 offset:8736
	v_cvt_pk_bf16_f32 v100, v100, v101
	s_waitcnt lgkmcnt(3)
	v_mfma_f32_32x32x16_bf16 v[48:63], v[8:11], v[4:7], 0
	v_cvt_pk_bf16_f32 v101, v102, v103
	s_waitcnt lgkmcnt(1)
	v_mfma_f32_32x32x16_bf16 v[32:47], v[0:3], v[4:7], 0
	ds_read_b128 v[0:3], v121 offset:17408
	ds_read_b128 v[134:137], v121 offset:17440
	v_cvt_pk_bf16_f32 v102, v96, v97
	s_waitcnt lgkmcnt(1)
	v_mfma_f32_32x32x16_bf16 v[16:31], v[0:3], v[4:7], 0
	ds_read_b128 v[0:3], v121 offset:26112
	ds_read_b128 v[138:141], v121 offset:26144
	ds_read_b128 v[112:115], v121 offset:64
	ds_read_b128 v[104:107], v121 offset:96
	v_cvt_pk_bf16_f32 v103, v98, v99
	v_or_b32_e32 v68, 64, v120
	v_cmp_le_u32_e32 vcc, v68, v125
	s_waitcnt lgkmcnt(3)
	v_mfma_f32_32x32x16_bf16 v[0:15], v[0:3], v[4:7], 0
	s_waitcnt vmcnt(2)
	v_cndmask_b32_e32 v92, 0, v92, vcc
	v_cmp_lt_u32_e32 vcc, v68, v125
	s_nop 1
	v_cndmask_b32_e32 v68, 0, v93, vcc
	v_mfma_f32_32x32x16_bf16 v[48:63], v[126:129], v[116:119], v[48:63]
	v_cvt_pk_bf16_f32 v92, v92, v68
	v_or_b32_e32 v68, 0x42, v120
	v_cmp_le_u32_e32 vcc, v68, v125
	v_mfma_f32_32x32x16_bf16 v[32:47], v[130:133], v[116:119], v[32:47]
	v_or_b32_e32 v93, 0x43, v120
	v_cndmask_b32_e32 v68, 0, v94, vcc
	v_cmp_le_u32_e32 vcc, v93, v125
	v_cndmask_b32_e32 v93, 0, v95, vcc
	v_mfma_f32_32x32x16_bf16 v[16:31], v[134:137], v[116:119], v[16:31]
	v_cvt_pk_bf16_f32 v93, v68, v93
	v_or_b32_e32 v68, 0x44, v120
	v_cmp_le_u32_e32 vcc, v68, v125
	s_waitcnt lgkmcnt(2)
	v_mfma_f32_32x32x16_bf16 v[0:15], v[138:141], v[116:119], v[0:15]
	v_cndmask_b32_e32 v68, 0, v88, vcc
	v_or_b32_e32 v88, 0x45, v120
	v_cmp_le_u32_e32 vcc, v88, v125
	s_nop 1
	v_cndmask_b32_e32 v88, 0, v89, vcc
	s_waitcnt lgkmcnt(1)
	v_mfma_f32_32x32x16_bf16 v[48:63], v[112:115], v[108:111], v[48:63]
	ds_read_b128 v[112:115], v121 offset:8768
	ds_read_b128 v[116:119], v121 offset:8800
	v_cvt_pk_bf16_f32 v94, v68, v88
	v_or_b32_e32 v68, 0x46, v120
	s_waitcnt lgkmcnt(1)
	v_mfma_f32_32x32x16_bf16 v[32:47], v[112:115], v[108:111], v[32:47]
	ds_read_b128 v[112:115], v121 offset:17472
	ds_read_b128 v[126:129], v121 offset:17504
	v_cmp_le_u32_e32 vcc, v68, v125
	v_or_b32_e32 v88, 0x47, v120
	s_nop 0
	v_cndmask_b32_e32 v68, 0, v90, vcc
	v_cmp_le_u32_e32 vcc, v88, v125
	s_waitcnt lgkmcnt(1)
	v_mfma_f32_32x32x16_bf16 v[16:31], v[112:115], v[108:111], v[16:31]
	ds_read_b128 v[112:115], v121 offset:26176
	ds_read_b128 v[130:133], v121 offset:26208
	ds_read_b128 v[96:99], v121 offset:128
	v_cndmask_b32_e32 v88, 0, v91, vcc
	v_mfma_f32_32x32x16_bf16 v[48:63], v[104:107], v[100:103], v[48:63]
	v_cvt_pk_bf16_f32 v95, v68, v88
	ds_read_b128 v[88:91], v121 offset:160
	v_xor_b32_e32 v68, 32, v124
	v_add_lshl_u32 v68, v68, s37, 2
	v_mov_b64_e32 v[104:105], s[22:23]
	s_waitcnt lgkmcnt(3)
	v_mfma_f32_32x32x16_bf16 v[0:15], v[112:115], v[108:111], v[0:15]
	v_or_b32_e32 v110, s18, v125
	v_mov_b32_e32 v111, s19
	s_waitcnt lgkmcnt(1)
	v_mfma_f32_32x32x16_bf16 v[48:63], v[96:99], v[92:95], v[48:63]
	ds_read_b128 v[96:99], v121 offset:8832
	v_mfma_f32_32x32x16_bf16 v[32:47], v[116:119], v[100:103], v[32:47]
	v_mfma_f32_32x32x16_bf16 v[16:31], v[126:129], v[100:103], v[16:31]
	v_mfma_f32_32x32x16_bf16 v[0:15], v[130:133], v[100:103], v[0:15]
	ds_read_b128 v[100:103], v121 offset:17536
	ds_read_b128 v[114:117], v121 offset:8864
	global_load_dword v68, v68, s[14:15] offset:256
	s_movk_i32 s14, 0x1400
	s_waitcnt lgkmcnt(2)
	v_mfma_f32_32x32x16_bf16 v[32:47], v[96:99], v[92:95], v[32:47]
	ds_read_b128 v[96:99], v121 offset:26240
	ds_read_b128 v[126:129], v121 offset:17568
	ds_read_b128 v[130:133], v121 offset:26272
	s_waitcnt lgkmcnt(4)
	v_mfma_f32_32x32x16_bf16 v[16:31], v[100:103], v[92:95], v[16:31]
	v_mad_u64_u32 v[100:101], s[14:15], v110, s14, v[104:105]
	v_mov_b32_e32 v102, 0x1400
	v_mad_u32_u24 v101, s19, v102, v101
	v_lshl_add_u64 v[100:101], v[100:101], 0, s[16:17]
	s_waitcnt lgkmcnt(2)
	v_mfma_f32_32x32x16_bf16 v[0:15], v[96:99], v[92:95], v[0:15]
	v_or_b32_e32 v92, 0x50, v120
	v_cmp_le_u32_e32 vcc, v92, v125
	s_waitcnt vmcnt(1)
	s_nop 0
	v_cndmask_b32_e32 v84, 0, v84, vcc
	v_cmp_lt_u32_e32 vcc, v92, v125
	v_cndmask_b32_e32 v85, 0, v85, vcc
	v_cvt_pk_bf16_f32 v134, v84, v85
	v_or_b32_e32 v84, 0x52, v120
	v_cmp_le_u32_e32 vcc, v84, v125
	v_or_b32_e32 v85, 0x53, v120
	s_nop 0
	v_cndmask_b32_e32 v84, 0, v86, vcc
	v_cmp_le_u32_e32 vcc, v85, v125
	v_cndmask_b32_e32 v85, 0, v87, vcc
	v_cvt_pk_bf16_f32 v135, v84, v85
	v_or_b32_e32 v84, 0x54, v120
	v_cmp_le_u32_e32 vcc, v84, v125
	v_or_b32_e32 v84, 0x55, v120
	s_nop 0
	v_cndmask_b32_e32 v80, 0, v80, vcc
	v_cmp_le_u32_e32 vcc, v84, v125
	v_cndmask_b32_e32 v81, 0, v81, vcc
	v_cvt_pk_bf16_f32 v136, v80, v81
	v_or_b32_e32 v80, 0x56, v120
	v_cmp_le_u32_e32 vcc, v80, v125
	v_or_b32_e32 v81, 0x57, v120
	s_nop 0
	v_cndmask_b32_e32 v80, 0, v82, vcc
	v_cmp_le_u32_e32 vcc, v81, v125
	v_cndmask_b32_e32 v81, 0, v83, vcc
	v_cvt_pk_bf16_f32 v137, v80, v81
	v_mov_b32_e32 v81, 0
	v_mov_b32_e32 v80, v122
	v_lshl_add_u64 v[80:81], v[100:101], 0, v[80:81]
	v_mfma_f32_32x32x16_bf16 v[48:63], v[88:91], v[134:137], v[48:63]
	v_bfe_u32 v174, v224, 5, 1
	v_lshlrev_b32_e32 v174, 3, v174
	v_mov_b32_e32 v175, 0
	v_lshl_add_u64 v[172:173], v[80:81], 0, v[174:175]
	global_load_dwordx4 v[140:143], v[172:173], off offset:3072
	global_load_dwordx4 v[144:147], v[172:173], off offset:3104
	global_load_dwordx4 v[148:151], v[172:173], off offset:3136
	global_load_dwordx4 v[152:155], v[172:173], off offset:3168
	global_load_dwordx4 v[156:159], v[172:173], off offset:3200
	global_load_dwordx4 v[160:163], v[172:173], off offset:3232
	global_load_dwordx4 v[164:167], v[172:173], off offset:3264
	global_load_dwordx4 v[168:171], v[172:173], off offset:3296
	s_nop 0
	s_and_b64 vcc, exec, s[8:9]
	v_mfma_f32_32x32x16_bf16 v[32:47], v[114:117], v[134:137], v[32:47]
	s_waitcnt lgkmcnt(1)
	v_mfma_f32_32x32x16_bf16 v[16:31], v[126:129], v[134:137], v[16:31]
	s_waitcnt lgkmcnt(0)
	v_mfma_f32_32x32x16_bf16 v[0:15], v[130:133], v[134:137], v[0:15]
	s_cbranch_vccnz .LBB0_416
	v_or_b32_e32 v114, 0x60, v120
	v_cmp_le_u32_e32 vcc, v114, v125
	s_nop 1
	v_cndmask_b32_e32 v76, 0, v76, vcc
	v_cmp_lt_u32_e32 vcc, v114, v125
	v_cndmask_b32_e32 v77, 0, v77, vcc
	v_cvt_pk_bf16_f32 v76, v76, v77
	v_or_b32_e32 v77, 0x62, v120
	v_cmp_le_u32_e32 vcc, v77, v125
	ds_read_b128 v[114:117], v121 offset:192
	s_nop 0
	v_cndmask_b32_e32 v77, 0, v78, vcc
	v_or_b32_e32 v78, 0x63, v120
	v_cmp_le_u32_e32 vcc, v78, v125
	s_nop 1
	v_cndmask_b32_e32 v78, 0, v79, vcc
	v_cvt_pk_bf16_f32 v77, v77, v78
	v_or_b32_e32 v78, 0x64, v120
	v_cmp_le_u32_e32 vcc, v78, v125
	v_or_b32_e32 v78, 0x65, v120
	s_nop 0
	v_cndmask_b32_e32 v72, 0, v72, vcc
	v_cmp_le_u32_e32 vcc, v78, v125
	v_cndmask_b32_e32 v73, 0, v73, vcc
	v_cvt_pk_bf16_f32 v78, v72, v73
	v_or_b32_e32 v72, 0x66, v120
	v_cmp_le_u32_e32 vcc, v72, v125
	v_or_b32_e32 v73, 0x67, v120
	s_nop 0
	v_cndmask_b32_e32 v72, 0, v74, vcc
	v_cmp_le_u32_e32 vcc, v73, v125
	v_cndmask_b32_e32 v73, 0, v75, vcc
	v_cvt_pk_bf16_f32 v79, v72, v73
	ds_read_b128 v[72:75], v121 offset:8896
	s_waitcnt lgkmcnt(1)
	v_mfma_f32_32x32x16_bf16 v[48:63], v[114:117], v[76:79], v[48:63]
	s_waitcnt lgkmcnt(0)
	v_mfma_f32_32x32x16_bf16 v[32:47], v[72:75], v[76:79], v[32:47]
	ds_read_b128 v[72:75], v121 offset:17600
	ds_read_b128 v[114:117], v121 offset:26304
	s_waitcnt lgkmcnt(1)
	v_mfma_f32_32x32x16_bf16 v[16:31], v[72:75], v[76:79], v[16:31]
	s_waitcnt lgkmcnt(0)
	v_mfma_f32_32x32x16_bf16 v[0:15], v[114:117], v[76:79], v[0:15]
.LBB0_416:
	s_and_b64 vcc, exec, s[8:9]
	s_cbranch_vccnz .LBB0_418
	v_or_b32_e32 v72, 0x70, v120
	v_cmp_le_u32_e32 vcc, v72, v125
	s_movk_i32 s8, 0x7fff
	s_mov_b32 s9, 0xffff0000
	v_cndmask_b32_e32 v73, 0, v123, vcc
	v_cmp_lt_u32_e32 vcc, v72, v125
	v_cndmask_b32_e32 v69, 0, v69, vcc
	v_cvt_pk_bf16_f32 v72, v73, v69
	v_or_b32_e32 v69, 0x72, v120
	v_cmp_le_u32_e32 vcc, v69, v125
	ds_read_b128 v[76:79], v121 offset:224
	s_nop 0
	v_cndmask_b32_e32 v69, 0, v70, vcc
	v_or_b32_e32 v70, 0x73, v120
	v_cmp_le_u32_e32 vcc, v70, v125
	s_nop 1
	v_cndmask_b32_e32 v70, 0, v71, vcc
	v_cvt_pk_bf16_f32 v73, v69, v70
	v_or_b32_e32 v69, 0x74, v120
	v_cmp_le_u32_e32 vcc, v69, v125
	v_or_b32_e32 v69, 0x75, v120
	s_nop 0
	v_cndmask_b32_e32 v64, 0, v64, vcc
	v_cmp_le_u32_e32 vcc, v69, v125
	v_cndmask_b32_e32 v65, 0, v65, vcc
	v_cvt_pk_bf16_f32 v74, v64, v65
	v_or_b32_e32 v64, 0x76, v120
	v_cmp_le_u32_e32 vcc, v64, v125
	v_or_b32_e32 v65, 0x77, v120
	s_nop 0
	v_cndmask_b32_e32 v64, 0, v66, vcc
	v_cmp_le_u32_e32 vcc, v65, v125
	v_cndmask_b32_e32 v65, 0, v67, vcc
	v_cvt_pk_bf16_f32 v75, v64, v65
	ds_read_b128 v[64:67], v121 offset:8928
	s_waitcnt lgkmcnt(1)
	v_mfma_f32_32x32x16_bf16 v[48:63], v[76:79], v[72:75], v[48:63]
	s_waitcnt lgkmcnt(0)
	v_mfma_f32_32x32x16_bf16 v[32:47], v[64:67], v[72:75], v[32:47]
	ds_read_b128 v[64:67], v121 offset:17632
	ds_read_b128 v[76:79], v121 offset:26336
	s_waitcnt lgkmcnt(1)
	v_mfma_f32_32x32x16_bf16 v[16:31], v[64:67], v[72:75], v[16:31]
	s_waitcnt lgkmcnt(0)
	v_mfma_f32_32x32x16_bf16 v[0:15], v[76:79], v[72:75], v[0:15]

.LBB0_1276:
	v_cmp_le_u32_e32 vcc, v120, v124
	s_movk_i32 s12, 0x7fff
	s_mov_b32 s13, 0xffff0000
	s_waitcnt vmcnt(2)
	v_cndmask_b32_e32 v4, 0, v4, vcc
	v_cmp_lt_u32_e32 vcc, v120, v124
	v_cndmask_b32_e32 v5, 0, v5, vcc
	v_cvt_pk_bf16_f32 v4, v4, v5
	v_or_b32_e32 v5, 2, v120
	v_cmp_le_u32_e32 vcc, v5, v124
	v_lshl_add_u32 v119, v120, 1, s26
	s_movk_i32 s16, 0x110
	v_cndmask_b32_e32 v5, 0, v6, vcc
	v_or_b32_e32 v6, 3, v120
	v_cmp_le_u32_e32 vcc, v6, v124
	v_mad_u32_u24 v88, v118, s16, v119
	ds_read_b128 v[12:15], v88
	ds_read_b128 v[92:95], v88 offset:32
	v_cndmask_b32_e32 v6, 0, v7, vcc
	v_cvt_pk_bf16_f32 v5, v5, v6
	v_or_b32_e32 v6, 4, v120
	v_cmp_le_u32_e32 vcc, v6, v124
	v_or_b32_e32 v6, 5, v120
	v_lshlrev_b32_e32 v8, 2, v10
	v_cndmask_b32_e32 v0, 0, v0, vcc
	v_cmp_le_u32_e32 vcc, v6, v124
	v_cndmask_b32_e32 v1, 0, v1, vcc
	v_cvt_pk_bf16_f32 v6, v0, v1
	v_or_b32_e32 v0, 6, v120
	v_cmp_le_u32_e32 vcc, v0, v124
	v_or_b32_e32 v1, 7, v120
	v_or_b32_e32 v114, s40, v124
	v_cndmask_b32_e32 v0, 0, v2, vcc
	v_cmp_le_u32_e32 vcc, v1, v124
	v_cndmask_b32_e32 v1, 0, v3, vcc
	v_cvt_pk_bf16_f32 v7, v0, v1
	ds_read_b128 v[0:3], v88 offset:8704
	ds_read_b128 v[96:99], v88 offset:8736
	s_waitcnt lgkmcnt(1)
	v_mfma_f32_32x32x16_bf16 v[32:47], v[0:3], v[4:7], 0
	ds_read_b128 v[0:3], v88 offset:17408
	global_load_dword v68, v8, s[18:19] offset:2048
	ds_read_b128 v[8:11], v88 offset:26112
	ds_read_b128 v[126:129], v88 offset:17440
	ds_read_b128 v[130:133], v88 offset:26144
	v_or_b32_e32 v88, 16, v120
	v_cmp_le_u32_e32 vcc, v88, v124
	s_movk_i32 s16, 0x1400
	v_mfma_f32_32x32x16_bf16 v[48:63], v[12:15], v[4:7], 0
	s_waitcnt vmcnt(1)
	v_cndmask_b32_e32 v84, 0, v84, vcc
	v_cmp_lt_u32_e32 vcc, v88, v124
	v_cndmask_b32_e32 v85, 0, v85, vcc
	v_cvt_pk_bf16_f32 v134, v84, v85
	v_or_b32_e32 v84, 18, v120
	v_cmp_le_u32_e32 vcc, v84, v124
	v_or_b32_e32 v85, 19, v120
	s_waitcnt lgkmcnt(3)
	v_mfma_f32_32x32x16_bf16 v[16:31], v[0:3], v[4:7], 0
	v_cndmask_b32_e32 v84, 0, v86, vcc
	v_cmp_le_u32_e32 vcc, v85, v124
	v_cndmask_b32_e32 v85, 0, v87, vcc
	v_cvt_pk_bf16_f32 v135, v84, v85
	v_or_b32_e32 v84, 20, v120
	v_cmp_le_u32_e32 vcc, v84, v124
	v_or_b32_e32 v84, 21, v120
	v_mov_b64_e32 v[0:1], s[20:21]
	v_cndmask_b32_e32 v80, 0, v80, vcc
	v_cmp_le_u32_e32 vcc, v84, v124
	v_cndmask_b32_e32 v81, 0, v81, vcc
	v_cvt_pk_bf16_f32 v136, v80, v81
	v_or_b32_e32 v80, 22, v120
	v_cmp_le_u32_e32 vcc, v80, v124
	v_or_b32_e32 v81, 23, v120
	v_mad_u64_u32 v[100:101], s[16:17], v114, s16, v[0:1]
	v_cndmask_b32_e32 v80, 0, v82, vcc
	v_cmp_le_u32_e32 vcc, v81, v124
	v_mov_b32_e32 v102, 0x1400
	v_cndmask_b32_e32 v81, 0, v83, vcc
	v_mad_u32_u24 v101, s41, v102, v101
	v_mov_b32_e32 v121, 0
	v_cvt_pk_bf16_f32 v137, v80, v81
	v_lshl_add_u64 v[80:81], v[100:101], 0, s[38:39]
	v_lshl_add_u64 v[80:81], v[80:81], 0, v[120:121]
	v_mfma_f32_32x32x16_bf16 v[48:63], v[92:95], v[134:137], v[48:63]
	v_bfe_u32 v174, v224, 5, 1
	v_lshlrev_b32_e32 v174, 3, v174
	v_mov_b32_e32 v175, 0
	v_lshl_add_u64 v[172:173], v[80:81], 0, v[174:175]
	global_load_dwordx4 v[140:143], v[172:173], off offset:3072
	global_load_dwordx4 v[144:147], v[172:173], off offset:3104
	v_mul_u32_u24_e32 v118, 0x110, v118
	v_lshlrev_b32_e32 v88, 2, v115
	v_mov_b32_e32 v115, s41
	s_and_b64 vcc, exec, s[10:11]
	v_add_u32_e32 v121, v119, v118
	v_mfma_f32_32x32x16_bf16 v[32:47], v[96:99], v[134:137], v[32:47]
	global_load_dwordx4 v[148:151], v[172:173], off offset:3136
	global_load_dwordx4 v[152:155], v[172:173], off offset:3168
	global_load_dwordx4 v[156:159], v[172:173], off offset:3200
	global_load_dwordx4 v[160:163], v[172:173], off offset:3232
	global_load_dwordx4 v[164:167], v[172:173], off offset:3264
	global_load_dwordx4 v[168:171], v[172:173], off offset:3296
	s_nop 0
	s_waitcnt lgkmcnt(2)
	v_mfma_f32_32x32x16_bf16 v[0:15], v[8:11], v[4:7], 0
	s_waitcnt lgkmcnt(1)
	v_mfma_f32_32x32x16_bf16 v[16:31], v[126:129], v[134:137], v[16:31]
	s_waitcnt lgkmcnt(0)
	v_mfma_f32_32x32x16_bf16 v[0:15], v[130:133], v[134:137], v[0:15]
	s_cbranch_vccnz .LBB0_1278
	v_or_b32_e32 v118, 32, v120
	v_cmp_le_u32_e32 vcc, v118, v124
	ds_read_b128 v[126:129], v121 offset:64
	s_nop 0
	v_cndmask_b32_e32 v76, 0, v76, vcc
	v_cmp_lt_u32_e32 vcc, v118, v124
	v_cndmask_b32_e32 v77, 0, v77, vcc
	v_cvt_pk_bf16_f32 v76, v76, v77
	v_or_b32_e32 v77, 34, v120
	v_cmp_le_u32_e32 vcc, v77, v124
	s_nop 1
	v_cndmask_b32_e32 v77, 0, v78, vcc
	v_or_b32_e32 v78, 35, v120
	v_cmp_le_u32_e32 vcc, v78, v124
	s_nop 1
	v_cndmask_b32_e32 v78, 0, v79, vcc
	v_cvt_pk_bf16_f32 v77, v77, v78
	v_or_b32_e32 v78, 36, v120
	v_cmp_le_u32_e32 vcc, v78, v124
	v_or_b32_e32 v78, 37, v120
	s_nop 0
	v_cndmask_b32_e32 v72, 0, v72, vcc
	v_cmp_le_u32_e32 vcc, v78, v124
	v_cndmask_b32_e32 v73, 0, v73, vcc
	v_cvt_pk_bf16_f32 v78, v72, v73
	v_or_b32_e32 v72, 38, v120
	v_cmp_le_u32_e32 vcc, v72, v124
	v_or_b32_e32 v73, 39, v120
	s_nop 0
	v_cndmask_b32_e32 v72, 0, v74, vcc
	v_cmp_le_u32_e32 vcc, v73, v124
	v_cndmask_b32_e32 v73, 0, v75, vcc
	v_cvt_pk_bf16_f32 v79, v72, v73
	ds_read_b128 v[72:75], v121 offset:8768
	s_waitcnt lgkmcnt(1)
	v_mfma_f32_32x32x16_bf16 v[48:63], v[126:129], v[76:79], v[48:63]
	s_waitcnt lgkmcnt(0)
	v_mfma_f32_32x32x16_bf16 v[32:47], v[72:75], v[76:79], v[32:47]
	ds_read_b128 v[72:75], v121 offset:17472
	ds_read_b128 v[126:129], v121 offset:26176
	s_waitcnt lgkmcnt(1)
	v_mfma_f32_32x32x16_bf16 v[16:31], v[72:75], v[76:79], v[16:31]
	s_waitcnt lgkmcnt(0)
	v_mfma_f32_32x32x16_bf16 v[0:15], v[126:129], v[76:79], v[0:15]
.LBB0_1278:
	s_and_b64 vcc, exec, s[10:11]
	s_cbranch_vccnz .LBB0_1280
	v_or_b32_e32 v72, 48, v120
	v_cmp_le_u32_e32 vcc, v72, v124
	s_movk_i32 s10, 0x7fff
	s_mov_b32 s11, 0xffff0000
	v_cndmask_b32_e32 v73, 0, v89, vcc
	v_cmp_lt_u32_e32 vcc, v72, v124
	v_cndmask_b32_e32 v69, 0, v69, vcc
	v_cvt_pk_bf16_f32 v72, v73, v69
	v_or_b32_e32 v69, 50, v120
	v_cmp_le_u32_e32 vcc, v69, v124
	ds_read_b128 v[76:79], v121 offset:96
	s_nop 0
	v_cndmask_b32_e32 v69, 0, v70, vcc
	v_or_b32_e32 v70, 51, v120
	v_cmp_le_u32_e32 vcc, v70, v124
	s_nop 1
	v_cndmask_b32_e32 v70, 0, v71, vcc
	v_cvt_pk_bf16_f32 v73, v69, v70
	v_or_b32_e32 v69, 52, v120
	v_cmp_le_u32_e32 vcc, v69, v124
	v_or_b32_e32 v69, 53, v120
	s_nop 0
	v_cndmask_b32_e32 v64, 0, v64, vcc
	v_cmp_le_u32_e32 vcc, v69, v124
	v_cndmask_b32_e32 v65, 0, v65, vcc
	v_cvt_pk_bf16_f32 v74, v64, v65
	v_or_b32_e32 v64, 54, v120
	v_cmp_le_u32_e32 vcc, v64, v124
	v_or_b32_e32 v65, 55, v120
	s_nop 0
	v_cndmask_b32_e32 v64, 0, v66, vcc
	v_cmp_le_u32_e32 vcc, v65, v124
	v_cndmask_b32_e32 v65, 0, v67, vcc
	v_cvt_pk_bf16_f32 v75, v64, v65
	ds_read_b128 v[64:67], v121 offset:8800
	s_waitcnt lgkmcnt(1)
	v_mfma_f32_32x32x16_bf16 v[48:63], v[76:79], v[72:75], v[48:63]
	s_waitcnt lgkmcnt(0)
	v_mfma_f32_32x32x16_bf16 v[32:47], v[64:67], v[72:75], v[32:47]
	ds_read_b128 v[64:67], v121 offset:17504
	ds_read_b128 v[76:79], v121 offset:26208
	s_waitcnt lgkmcnt(1)
	v_mfma_f32_32x32x16_bf16 v[16:31], v[64:67], v[72:75], v[16:31]
	s_waitcnt lgkmcnt(0)
	v_mfma_f32_32x32x16_bf16 v[0:15], v[76:79], v[72:75], v[0:15]

.LBB0_1284:
	s_movk_i32 s14, 0x7fff
	s_waitcnt vmcnt(8)
	s_mov_b32 s15, 0xffff0000
	v_cvt_pk_bf16_f32 v116, v116, v117
	v_cvt_pk_bf16_f32 v117, v118, v119
	v_cvt_pk_bf16_f32 v118, v112, v113
	v_cvt_pk_bf16_f32 v119, v114, v115
	s_waitcnt vmcnt(6)
	v_cvt_pk_bf16_f32 v108, v108, v109
	v_cvt_pk_bf16_f32 v4, v4, v5
	v_cvt_pk_bf16_f32 v109, v110, v111
	v_cvt_pk_bf16_f32 v5, v6, v7
	ds_read_b128 v[8:11], v121
	ds_read_b128 v[126:129], v121 offset:32
	v_cvt_pk_bf16_f32 v110, v104, v105
	v_cvt_pk_bf16_f32 v6, v0, v1
	v_cvt_pk_bf16_f32 v111, v106, v107
	s_waitcnt vmcnt(4)
	v_cvt_pk_bf16_f32 v7, v2, v3
	ds_read_b128 v[0:3], v121 offset:8704
	ds_read_b128 v[130:133], v121 offset:8736
	v_cvt_pk_bf16_f32 v100, v100, v101
	s_waitcnt lgkmcnt(3)
	v_mfma_f32_32x32x16_bf16 v[48:63], v[8:11], v[4:7], 0
	v_cvt_pk_bf16_f32 v101, v102, v103
	s_waitcnt lgkmcnt(1)
	v_mfma_f32_32x32x16_bf16 v[32:47], v[0:3], v[4:7], 0
	ds_read_b128 v[0:3], v121 offset:17408
	ds_read_b128 v[134:137], v121 offset:17440
	v_cvt_pk_bf16_f32 v102, v96, v97
	s_waitcnt lgkmcnt(1)
	v_mfma_f32_32x32x16_bf16 v[16:31], v[0:3], v[4:7], 0
	ds_read_b128 v[0:3], v121 offset:26112
	ds_read_b128 v[138:141], v121 offset:26144
	ds_read_b128 v[112:115], v121 offset:64
	ds_read_b128 v[104:107], v121 offset:96
	v_cvt_pk_bf16_f32 v103, v98, v99
	v_or_b32_e32 v68, 64, v120
	v_cmp_le_u32_e32 vcc, v68, v125
	s_waitcnt lgkmcnt(3)
	v_mfma_f32_32x32x16_bf16 v[0:15], v[0:3], v[4:7], 0
	s_movk_i32 s16, 0x1400
	s_waitcnt vmcnt(2)
	v_cndmask_b32_e32 v92, 0, v92, vcc
	v_cmp_lt_u32_e32 vcc, v68, v125
	s_nop 1
	v_cndmask_b32_e32 v68, 0, v93, vcc
	v_mfma_f32_32x32x16_bf16 v[48:63], v[126:129], v[116:119], v[48:63]
	v_cvt_pk_bf16_f32 v92, v92, v68
	v_or_b32_e32 v68, 0x42, v120
	v_cmp_le_u32_e32 vcc, v68, v125
	v_mfma_f32_32x32x16_bf16 v[32:47], v[130:133], v[116:119], v[32:47]
	v_or_b32_e32 v93, 0x43, v120
	v_cndmask_b32_e32 v68, 0, v94, vcc
	v_cmp_le_u32_e32 vcc, v93, v125
	v_cndmask_b32_e32 v93, 0, v95, vcc
	v_mfma_f32_32x32x16_bf16 v[16:31], v[134:137], v[116:119], v[16:31]
	v_cvt_pk_bf16_f32 v93, v68, v93
	v_or_b32_e32 v68, 0x44, v120
	v_cmp_le_u32_e32 vcc, v68, v125
	s_waitcnt lgkmcnt(2)
	v_mfma_f32_32x32x16_bf16 v[0:15], v[138:141], v[116:119], v[0:15]
	v_cndmask_b32_e32 v68, 0, v88, vcc
	v_or_b32_e32 v88, 0x45, v120
	v_cmp_le_u32_e32 vcc, v88, v125
	s_nop 1
	v_cndmask_b32_e32 v88, 0, v89, vcc
	s_waitcnt lgkmcnt(1)
	v_mfma_f32_32x32x16_bf16 v[48:63], v[112:115], v[108:111], v[48:63]
	ds_read_b128 v[112:115], v121 offset:8768
	ds_read_b128 v[116:119], v121 offset:8800
	v_cvt_pk_bf16_f32 v94, v68, v88
	v_or_b32_e32 v68, 0x46, v120
	s_waitcnt lgkmcnt(1)
	v_mfma_f32_32x32x16_bf16 v[32:47], v[112:115], v[108:111], v[32:47]
	ds_read_b128 v[112:115], v121 offset:17472
	ds_read_b128 v[126:129], v121 offset:17504
	v_cmp_le_u32_e32 vcc, v68, v125
	v_or_b32_e32 v88, 0x47, v120
	s_nop 0
	v_cndmask_b32_e32 v68, 0, v90, vcc
	v_cmp_le_u32_e32 vcc, v88, v125
	s_waitcnt lgkmcnt(1)
	v_mfma_f32_32x32x16_bf16 v[16:31], v[112:115], v[108:111], v[16:31]
	ds_read_b128 v[112:115], v121 offset:26176
	ds_read_b128 v[130:133], v121 offset:26208
	ds_read_b128 v[96:99], v121 offset:128
	v_cndmask_b32_e32 v88, 0, v91, vcc
	v_mfma_f32_32x32x16_bf16 v[48:63], v[104:107], v[100:103], v[48:63]
	v_cvt_pk_bf16_f32 v95, v68, v88
	ds_read_b128 v[88:91], v121 offset:160
	v_xor_b32_e32 v68, 32, v124
	v_add_lshl_u32 v68, v68, s43, 2
	v_mov_b64_e32 v[104:105], s[20:21]
	s_waitcnt lgkmcnt(3)
	v_mfma_f32_32x32x16_bf16 v[0:15], v[112:115], v[108:111], v[0:15]
	v_or_b32_e32 v110, s40, v125
	v_mov_b32_e32 v111, s41
	s_waitcnt lgkmcnt(1)
	v_mfma_f32_32x32x16_bf16 v[48:63], v[96:99], v[92:95], v[48:63]
	ds_read_b128 v[96:99], v121 offset:8832
	v_mfma_f32_32x32x16_bf16 v[32:47], v[116:119], v[100:103], v[32:47]
	v_mfma_f32_32x32x16_bf16 v[16:31], v[126:129], v[100:103], v[16:31]
	v_mfma_f32_32x32x16_bf16 v[0:15], v[130:133], v[100:103], v[0:15]
	ds_read_b128 v[100:103], v121 offset:17536
	ds_read_b128 v[114:117], v121 offset:8864
	global_load_dword v68, v68, s[18:19] offset:2304
	s_waitcnt lgkmcnt(2)
	v_mfma_f32_32x32x16_bf16 v[32:47], v[96:99], v[92:95], v[32:47]
	ds_read_b128 v[96:99], v121 offset:26240
	ds_read_b128 v[126:129], v121 offset:17568
	ds_read_b128 v[130:133], v121 offset:26272
	s_waitcnt lgkmcnt(4)
	v_mfma_f32_32x32x16_bf16 v[16:31], v[100:103], v[92:95], v[16:31]
	v_mad_u64_u32 v[100:101], s[16:17], v110, s16, v[104:105]
	v_mov_b32_e32 v102, 0x1400
	v_mad_u32_u24 v101, s41, v102, v101
	v_lshl_add_u64 v[100:101], v[100:101], 0, s[38:39]
	s_waitcnt lgkmcnt(2)
	v_mfma_f32_32x32x16_bf16 v[0:15], v[96:99], v[92:95], v[0:15]
	v_or_b32_e32 v92, 0x50, v120
	v_cmp_le_u32_e32 vcc, v92, v125
	s_waitcnt vmcnt(1)
	s_nop 0
	v_cndmask_b32_e32 v84, 0, v84, vcc
	v_cmp_lt_u32_e32 vcc, v92, v125
	v_cndmask_b32_e32 v85, 0, v85, vcc
	v_cvt_pk_bf16_f32 v134, v84, v85
	v_or_b32_e32 v84, 0x52, v120
	v_cmp_le_u32_e32 vcc, v84, v125
	v_or_b32_e32 v85, 0x53, v120
	s_nop 0
	v_cndmask_b32_e32 v84, 0, v86, vcc
	v_cmp_le_u32_e32 vcc, v85, v125
	v_cndmask_b32_e32 v85, 0, v87, vcc
	v_cvt_pk_bf16_f32 v135, v84, v85
	v_or_b32_e32 v84, 0x54, v120
	v_cmp_le_u32_e32 vcc, v84, v125
	v_or_b32_e32 v84, 0x55, v120
	s_nop 0
	v_cndmask_b32_e32 v80, 0, v80, vcc
	v_cmp_le_u32_e32 vcc, v84, v125
	v_cndmask_b32_e32 v81, 0, v81, vcc
	v_cvt_pk_bf16_f32 v136, v80, v81
	v_or_b32_e32 v80, 0x56, v120
	v_cmp_le_u32_e32 vcc, v80, v125
	v_or_b32_e32 v81, 0x57, v120
	s_nop 0
	v_cndmask_b32_e32 v80, 0, v82, vcc
	v_cmp_le_u32_e32 vcc, v81, v125
	v_cndmask_b32_e32 v81, 0, v83, vcc
	v_cvt_pk_bf16_f32 v137, v80, v81
	v_mov_b32_e32 v81, 0
	v_mov_b32_e32 v80, v122
	v_lshl_add_u64 v[80:81], v[100:101], 0, v[80:81]
	v_mfma_f32_32x32x16_bf16 v[48:63], v[88:91], v[134:137], v[48:63]
	v_bfe_u32 v174, v224, 5, 1
	v_lshlrev_b32_e32 v174, 3, v174
	v_mov_b32_e32 v175, 0
	v_lshl_add_u64 v[172:173], v[80:81], 0, v[174:175]
	global_load_dwordx4 v[140:143], v[172:173], off offset:3072
	global_load_dwordx4 v[144:147], v[172:173], off offset:3104
	global_load_dwordx4 v[148:151], v[172:173], off offset:3136
	global_load_dwordx4 v[152:155], v[172:173], off offset:3168
	global_load_dwordx4 v[156:159], v[172:173], off offset:3200
	global_load_dwordx4 v[160:163], v[172:173], off offset:3232
	global_load_dwordx4 v[164:167], v[172:173], off offset:3264
	global_load_dwordx4 v[168:171], v[172:173], off offset:3296
	s_nop 0
	s_and_b64 vcc, exec, s[10:11]
	v_mfma_f32_32x32x16_bf16 v[32:47], v[114:117], v[134:137], v[32:47]
	s_waitcnt lgkmcnt(1)
	v_mfma_f32_32x32x16_bf16 v[16:31], v[126:129], v[134:137], v[16:31]
	s_waitcnt lgkmcnt(0)
	v_mfma_f32_32x32x16_bf16 v[0:15], v[130:133], v[134:137], v[0:15]
	s_cbranch_vccnz .LBB0_1286
	v_or_b32_e32 v114, 0x60, v120
	v_cmp_le_u32_e32 vcc, v114, v125
	s_nop 1
	v_cndmask_b32_e32 v76, 0, v76, vcc
	v_cmp_lt_u32_e32 vcc, v114, v125
	v_cndmask_b32_e32 v77, 0, v77, vcc
	v_cvt_pk_bf16_f32 v76, v76, v77
	v_or_b32_e32 v77, 0x62, v120
	v_cmp_le_u32_e32 vcc, v77, v125
	ds_read_b128 v[114:117], v121 offset:192
	s_nop 0
	v_cndmask_b32_e32 v77, 0, v78, vcc
	v_or_b32_e32 v78, 0x63, v120
	v_cmp_le_u32_e32 vcc, v78, v125
	s_nop 1
	v_cndmask_b32_e32 v78, 0, v79, vcc
	v_cvt_pk_bf16_f32 v77, v77, v78
	v_or_b32_e32 v78, 0x64, v120
	v_cmp_le_u32_e32 vcc, v78, v125
	v_or_b32_e32 v78, 0x65, v120
	s_nop 0
	v_cndmask_b32_e32 v72, 0, v72, vcc
	v_cmp_le_u32_e32 vcc, v78, v125
	v_cndmask_b32_e32 v73, 0, v73, vcc
	v_cvt_pk_bf16_f32 v78, v72, v73
	v_or_b32_e32 v72, 0x66, v120
	v_cmp_le_u32_e32 vcc, v72, v125
	v_or_b32_e32 v73, 0x67, v120
	s_nop 0
	v_cndmask_b32_e32 v72, 0, v74, vcc
	v_cmp_le_u32_e32 vcc, v73, v125
	v_cndmask_b32_e32 v73, 0, v75, vcc
	v_cvt_pk_bf16_f32 v79, v72, v73
	ds_read_b128 v[72:75], v121 offset:8896
	s_waitcnt lgkmcnt(1)
	v_mfma_f32_32x32x16_bf16 v[48:63], v[114:117], v[76:79], v[48:63]
	s_waitcnt lgkmcnt(0)
	v_mfma_f32_32x32x16_bf16 v[32:47], v[72:75], v[76:79], v[32:47]
	ds_read_b128 v[72:75], v121 offset:17600
	ds_read_b128 v[114:117], v121 offset:26304
	s_waitcnt lgkmcnt(1)
	v_mfma_f32_32x32x16_bf16 v[16:31], v[72:75], v[76:79], v[16:31]
	s_waitcnt lgkmcnt(0)
	v_mfma_f32_32x32x16_bf16 v[0:15], v[114:117], v[76:79], v[0:15]
.LBB0_1286:
	s_and_b64 vcc, exec, s[10:11]
	s_cbranch_vccnz .LBB0_1288
	v_or_b32_e32 v72, 0x70, v120
	v_cmp_le_u32_e32 vcc, v72, v125
	s_movk_i32 s10, 0x7fff
	s_mov_b32 s11, 0xffff0000
	v_cndmask_b32_e32 v73, 0, v123, vcc
	v_cmp_lt_u32_e32 vcc, v72, v125
	v_cndmask_b32_e32 v69, 0, v69, vcc
	v_cvt_pk_bf16_f32 v72, v73, v69
	v_or_b32_e32 v69, 0x72, v120
	v_cmp_le_u32_e32 vcc, v69, v125
	ds_read_b128 v[76:79], v121 offset:224
	s_nop 0
	v_cndmask_b32_e32 v69, 0, v70, vcc
	v_or_b32_e32 v70, 0x73, v120
	v_cmp_le_u32_e32 vcc, v70, v125
	s_nop 1
	v_cndmask_b32_e32 v70, 0, v71, vcc
	v_cvt_pk_bf16_f32 v73, v69, v70
	v_or_b32_e32 v69, 0x74, v120
	v_cmp_le_u32_e32 vcc, v69, v125
	v_or_b32_e32 v69, 0x75, v120
	s_nop 0
	v_cndmask_b32_e32 v64, 0, v64, vcc
	v_cmp_le_u32_e32 vcc, v69, v125
	v_cndmask_b32_e32 v65, 0, v65, vcc
	v_cvt_pk_bf16_f32 v74, v64, v65
	v_or_b32_e32 v64, 0x76, v120
	v_cmp_le_u32_e32 vcc, v64, v125
	v_or_b32_e32 v65, 0x77, v120
	s_nop 0
	v_cndmask_b32_e32 v64, 0, v66, vcc
	v_cmp_le_u32_e32 vcc, v65, v125
	v_cndmask_b32_e32 v65, 0, v67, vcc
	v_cvt_pk_bf16_f32 v75, v64, v65
	ds_read_b128 v[64:67], v121 offset:8928
	s_waitcnt lgkmcnt(1)
	v_mfma_f32_32x32x16_bf16 v[48:63], v[76:79], v[72:75], v[48:63]
	s_waitcnt lgkmcnt(0)
	v_mfma_f32_32x32x16_bf16 v[32:47], v[64:67], v[72:75], v[32:47]
	ds_read_b128 v[64:67], v121 offset:17632
	ds_read_b128 v[76:79], v121 offset:26336
	s_waitcnt lgkmcnt(1)
	v_mfma_f32_32x32x16_bf16 v[16:31], v[64:67], v[72:75], v[16:31]
	s_waitcnt lgkmcnt(0)
	v_mfma_f32_32x32x16_bf16 v[0:15], v[76:79], v[72:75], v[0:15]
